# cv8 + G1/G5 K-loop LDS-DMA issue rebalanced from 2/6/2/6 to 4/4/4/4 per load segment (A-half-0 stages moved one segment later), waits 8/6/8/6
# speedup vs baseline: 1.0131x; 1.0131x over previous
.LBB0_306:
	s_add_u32 s38, s36, 0xfff80080
	s_addc_u32 s39, s37, -1
	s_add_i32 s45, 0, 0x10000
	s_cmp_eq_u32 s27, 28
	s_cselect_b32 s43, s9, s39
	s_cselect_b32 s42, s14, s38
	v_add_u32_e32 v34, s45, v170
	s_cselect_b32 s39, s16, s26
	s_cselect_b32 s38, s17, s25
	s_add_i32 s47, 0, 0x14000
	ds_read_b128 v[160:163], v34
	ds_read_b128 v[164:167], v34 offset:1024
	ds_read_b128 v[174:177], v34 offset:2048
	ds_read_b128 v[184:187], v34 offset:3072
	v_add_u32_e32 v34, s47, v170
	ds_read_b128 v[188:191], v34
	ds_read_b128 v[192:195], v34 offset:1024
	ds_read_b128 v[196:199], v34 offset:2048
	ds_read_b128 v[200:203], v34 offset:3072
	ds_read_b128 v[214:217], v173
	ds_read_b128 v[218:221], v173 offset:1024
	ds_read_b128 v[222:225], v173 offset:2048
	ds_read_b128 v[226:229], v173 offset:3072
	ds_read_b128 v[230:233], v173 offset:4096
	ds_read_b128 v[234:237], v173 offset:5120
	ds_read_b128 v[238:241], v173 offset:6144
	ds_read_b128 v[242:245], v173 offset:7168
	s_cmp_lg_u32 s27, -2
	s_cbranch_scc0 .Lr306_nf
	v_lshl_add_u64 v[168:169], v[246:247], 0, s[22:23]
	s_mov_b32 m0, s61
	s_nop 0
	global_load_lds_dwordx4 v[168:169], off
	v_lshl_add_u64 v[168:169], v[248:249], 0, s[22:23]
	s_mov_b32 m0, s64
	s_nop 0
	global_load_lds_dwordx4 v[168:169], off
.Lr306_nf:
	v_lshl_add_u64 v[168:169], s[36:37], 0, v[152:153]
	s_add_i32 m0, s35, 0xc000
	s_nop 0
	global_load_lds_dwordx4 v[168:169], off
	v_lshl_add_u64 v[168:169], s[36:37], 0, v[156:157]
	s_add_i32 m0, s35, 0xe000
	s_nop 0
	global_load_lds_dwordx4 v[168:169], off
	s_waitcnt vmcnt(8)
	s_waitcnt lgkmcnt(0)
	s_barrier
	s_setprio 1
	s_waitcnt lgkmcnt(0)
	v_mfma_f32_16x16x32_bf16 v[132:135], v[160:163], v[214:217], v[132:135]
	v_mfma_f32_16x16x32_bf16 v[128:131], v[174:177], v[214:217], v[128:131]
	v_mfma_f32_16x16x32_bf16 v[116:119], v[160:163], v[222:225], v[116:119]
	v_mfma_f32_16x16x32_bf16 v[112:115], v[174:177], v[222:225], v[112:115]
	v_mfma_f32_16x16x32_bf16 v[100:103], v[160:163], v[230:233], v[100:103]
	v_mfma_f32_16x16x32_bf16 v[96:99], v[174:177], v[230:233], v[96:99]
	v_mfma_f32_16x16x32_bf16 v[84:87], v[160:163], v[238:241], v[84:87]
	v_mfma_f32_16x16x32_bf16 v[80:83], v[174:177], v[238:241], v[80:83]
	v_mfma_f32_16x16x32_bf16 v[132:135], v[164:167], v[218:221], v[132:135]
	v_mfma_f32_16x16x32_bf16 v[128:131], v[184:187], v[218:221], v[128:131]
	v_mfma_f32_16x16x32_bf16 v[116:119], v[164:167], v[226:229], v[116:119]
	v_mfma_f32_16x16x32_bf16 v[112:115], v[184:187], v[226:229], v[112:115]
	v_mfma_f32_16x16x32_bf16 v[100:103], v[164:167], v[234:237], v[100:103]
	v_mfma_f32_16x16x32_bf16 v[96:99], v[184:187], v[234:237], v[96:99]
	v_mfma_f32_16x16x32_bf16 v[84:87], v[164:167], v[242:245], v[84:87]
	v_mfma_f32_16x16x32_bf16 v[80:83], v[184:187], v[242:245], v[80:83]
	s_setprio 0
	s_setprio 1
	v_mfma_f32_16x16x32_bf16 v[124:127], v[188:191], v[214:217], v[124:127]
	v_mfma_f32_16x16x32_bf16 v[120:123], v[196:199], v[214:217], v[120:123]
	v_mfma_f32_16x16x32_bf16 v[108:111], v[188:191], v[222:225], v[108:111]
	v_mfma_f32_16x16x32_bf16 v[104:107], v[196:199], v[222:225], v[104:107]
	v_mfma_f32_16x16x32_bf16 v[92:95], v[188:191], v[230:233], v[92:95]
	v_mfma_f32_16x16x32_bf16 v[88:91], v[196:199], v[230:233], v[88:91]
	v_mfma_f32_16x16x32_bf16 v[76:79], v[188:191], v[238:241], v[76:79]
	v_mfma_f32_16x16x32_bf16 v[72:75], v[196:199], v[238:241], v[72:75]
	v_mfma_f32_16x16x32_bf16 v[124:127], v[192:195], v[218:221], v[124:127]
	v_mfma_f32_16x16x32_bf16 v[120:123], v[200:203], v[218:221], v[120:123]
	v_mfma_f32_16x16x32_bf16 v[108:111], v[192:195], v[226:229], v[108:111]
	v_mfma_f32_16x16x32_bf16 v[104:107], v[200:203], v[226:229], v[104:107]
	v_mfma_f32_16x16x32_bf16 v[92:95], v[192:195], v[234:237], v[92:95]
	v_mfma_f32_16x16x32_bf16 v[88:91], v[200:203], v[234:237], v[88:91]
	v_mfma_f32_16x16x32_bf16 v[76:79], v[192:195], v[242:245], v[76:79]
	v_mfma_f32_16x16x32_bf16 v[72:75], v[200:203], v[242:245], v[72:75]
	s_setprio 0
	s_barrier
	s_add_i32 s45, s45, s53
	v_lshl_add_u64 v[168:169], s[38:39], 0, v[136:137]
	s_mov_b32 m0, s45
	ds_read_b128 v[214:217], v173 offset:16384
	ds_read_b128 v[218:221], v173 offset:17408
	ds_read_b128 v[222:225], v173 offset:18432
	ds_read_b128 v[226:229], v173 offset:19456
	ds_read_b128 v[230:233], v173 offset:20480
	ds_read_b128 v[234:237], v173 offset:21504
	ds_read_b128 v[238:241], v173 offset:22528
	ds_read_b128 v[242:245], v173 offset:23552
	global_load_lds_dwordx4 v[168:169], off
	s_add_i32 m0, s45, 0x2000
	s_add_u32 s70, s38, 0x80000
	v_lshl_add_u64 v[204:205], s[38:39], 0, v[140:141]
	s_addc_u32 s71, s39, 0
	s_add_i32 s45, s47, s53
	global_load_lds_dwordx4 v[204:205], off
	v_lshl_add_u64 v[246:247], s[70:71], 0, v[136:137]
	s_mov_b32 m0, s45
	v_lshl_add_u64 v[248:249], s[42:43], 0, v[138:139]
	global_load_lds_dwordx4 v[246:247], off
	v_lshl_add_u64 v[246:247], s[70:71], 0, v[140:141]
	s_add_i32 m0, s45, 0x2000
	s_nop 0
	global_load_lds_dwordx4 v[246:247], off
	v_lshl_add_u64 v[246:247], s[42:43], 0, v[14:15]
	s_waitcnt vmcnt(6)
	s_waitcnt lgkmcnt(0)
	s_barrier
	s_setprio 1
	s_waitcnt lgkmcnt(0)
	v_mfma_f32_16x16x32_bf16 v[68:71], v[160:163], v[214:217], v[68:71]
	v_mfma_f32_16x16x32_bf16 v[64:67], v[174:177], v[214:217], v[64:67]
	v_mfma_f32_16x16x32_bf16 v[52:55], v[160:163], v[222:225], v[52:55]
	v_mfma_f32_16x16x32_bf16 v[48:51], v[174:177], v[222:225], v[48:51]
	v_mfma_f32_16x16x32_bf16 v[36:39], v[160:163], v[230:233], v[36:39]
	v_mfma_f32_16x16x32_bf16 v[30:33], v[174:177], v[230:233], v[30:33]
	v_mfma_f32_16x16x32_bf16 v[18:21], v[160:163], v[238:241], v[18:21]
	v_mfma_f32_16x16x32_bf16 v[10:13], v[174:177], v[238:241], v[10:13]
	v_mfma_f32_16x16x32_bf16 v[68:71], v[164:167], v[218:221], v[68:71]
	v_mfma_f32_16x16x32_bf16 v[64:67], v[184:187], v[218:221], v[64:67]
	v_mfma_f32_16x16x32_bf16 v[52:55], v[164:167], v[226:229], v[52:55]
	v_mfma_f32_16x16x32_bf16 v[48:51], v[184:187], v[226:229], v[48:51]
	v_mfma_f32_16x16x32_bf16 v[36:39], v[164:167], v[234:237], v[36:39]
	v_mfma_f32_16x16x32_bf16 v[30:33], v[184:187], v[234:237], v[30:33]
	v_mfma_f32_16x16x32_bf16 v[18:21], v[164:167], v[242:245], v[18:21]
	v_mfma_f32_16x16x32_bf16 v[10:13], v[184:187], v[242:245], v[10:13]
	s_setprio 0
	s_setprio 1
	v_mfma_f32_16x16x32_bf16 v[60:63], v[188:191], v[214:217], v[60:63]
	v_mfma_f32_16x16x32_bf16 v[56:59], v[196:199], v[214:217], v[56:59]
	v_mfma_f32_16x16x32_bf16 v[44:47], v[188:191], v[222:225], v[44:47]
	v_mfma_f32_16x16x32_bf16 v[40:43], v[196:199], v[222:225], v[40:43]
	v_mfma_f32_16x16x32_bf16 v[26:29], v[188:191], v[230:233], v[26:29]
	v_mfma_f32_16x16x32_bf16 v[22:25], v[196:199], v[230:233], v[22:25]
	v_mfma_f32_16x16x32_bf16 v[6:9], v[188:191], v[238:241], v[6:9]
	v_mfma_f32_16x16x32_bf16 v[2:5], v[196:199], v[238:241], v[2:5]
	v_mfma_f32_16x16x32_bf16 v[60:63], v[192:195], v[218:221], v[60:63]
	v_mfma_f32_16x16x32_bf16 v[56:59], v[200:203], v[218:221], v[56:59]
	v_mfma_f32_16x16x32_bf16 v[44:47], v[192:195], v[226:229], v[44:47]
	v_mfma_f32_16x16x32_bf16 v[40:43], v[200:203], v[226:229], v[40:43]
	v_mfma_f32_16x16x32_bf16 v[26:29], v[192:195], v[234:237], v[26:29]
	v_mfma_f32_16x16x32_bf16 v[22:25], v[200:203], v[234:237], v[22:25]
	v_mfma_f32_16x16x32_bf16 v[6:9], v[192:195], v[242:245], v[6:9]
	v_mfma_f32_16x16x32_bf16 v[2:5], v[200:203], v[242:245], v[2:5]
	s_setprio 0
	s_barrier
	s_add_i32 s45, 0, 0x18000
	v_add_u32_e32 v34, s45, v170
	s_add_i32 s47, 0, 0x1c000
	ds_read_b128 v[160:163], v34
	ds_read_b128 v[164:167], v34 offset:1024
	ds_read_b128 v[174:177], v34 offset:2048
	ds_read_b128 v[184:187], v34 offset:3072
	v_add_u32_e32 v34, s47, v170
	ds_read_b128 v[188:191], v34
	ds_read_b128 v[192:195], v34 offset:1024
	ds_read_b128 v[196:199], v34 offset:2048
	ds_read_b128 v[200:203], v34 offset:3072
	s_add_u32 s42, s42, 0x80000
	s_addc_u32 s43, s43, 0
	s_mov_b32 m0, s55
	v_lshl_add_u64 v[250:251], s[42:43], 0, v[14:15]
	ds_read_b128 v[214:217], v173 offset:32768
	ds_read_b128 v[218:221], v173 offset:33792
	ds_read_b128 v[222:225], v173 offset:34816
	ds_read_b128 v[226:229], v173 offset:35840
	ds_read_b128 v[230:233], v173 offset:36864
	ds_read_b128 v[234:237], v173 offset:37888
	ds_read_b128 v[238:241], v173 offset:38912
	ds_read_b128 v[242:245], v173 offset:39936
	s_mov_b32 m0, s35
	s_nop 0
	global_load_lds_dwordx4 v[246:247], off
	s_mov_b32 m0, s54
	s_nop 0
	global_load_lds_dwordx4 v[248:249], off
	s_mov_b32 m0, s55
	s_nop 0
	global_load_lds_dwordx4 v[250:251], off
	v_lshl_add_u64 v[250:251], s[42:43], 0, v[138:139]
	s_mov_b32 m0, s60
	s_nop 0
	global_load_lds_dwordx4 v[250:251], off
	s_waitcnt vmcnt(8)
	s_waitcnt lgkmcnt(0)
	s_barrier
	s_setprio 1
	s_waitcnt lgkmcnt(0)
	v_mfma_f32_16x16x32_bf16 v[132:135], v[160:163], v[214:217], v[132:135]
	v_mfma_f32_16x16x32_bf16 v[128:131], v[174:177], v[214:217], v[128:131]
	v_mfma_f32_16x16x32_bf16 v[116:119], v[160:163], v[222:225], v[116:119]
	v_mfma_f32_16x16x32_bf16 v[112:115], v[174:177], v[222:225], v[112:115]
	v_mfma_f32_16x16x32_bf16 v[100:103], v[160:163], v[230:233], v[100:103]
	v_mfma_f32_16x16x32_bf16 v[96:99], v[174:177], v[230:233], v[96:99]
	v_mfma_f32_16x16x32_bf16 v[84:87], v[160:163], v[238:241], v[84:87]
	v_mfma_f32_16x16x32_bf16 v[80:83], v[174:177], v[238:241], v[80:83]
	v_mfma_f32_16x16x32_bf16 v[132:135], v[164:167], v[218:221], v[132:135]
	v_mfma_f32_16x16x32_bf16 v[128:131], v[184:187], v[218:221], v[128:131]
	v_mfma_f32_16x16x32_bf16 v[116:119], v[164:167], v[226:229], v[116:119]
	v_mfma_f32_16x16x32_bf16 v[112:115], v[184:187], v[226:229], v[112:115]
	v_mfma_f32_16x16x32_bf16 v[100:103], v[164:167], v[234:237], v[100:103]
	v_mfma_f32_16x16x32_bf16 v[96:99], v[184:187], v[234:237], v[96:99]
	v_mfma_f32_16x16x32_bf16 v[84:87], v[164:167], v[242:245], v[84:87]
	v_mfma_f32_16x16x32_bf16 v[80:83], v[184:187], v[242:245], v[80:83]
	s_setprio 0
	s_setprio 1
	v_mfma_f32_16x16x32_bf16 v[124:127], v[188:191], v[214:217], v[124:127]
	v_mfma_f32_16x16x32_bf16 v[120:123], v[196:199], v[214:217], v[120:123]
	v_mfma_f32_16x16x32_bf16 v[108:111], v[188:191], v[222:225], v[108:111]
	v_mfma_f32_16x16x32_bf16 v[104:107], v[196:199], v[222:225], v[104:107]
	v_mfma_f32_16x16x32_bf16 v[92:95], v[188:191], v[230:233], v[92:95]
	v_mfma_f32_16x16x32_bf16 v[88:91], v[196:199], v[230:233], v[88:91]
	v_mfma_f32_16x16x32_bf16 v[76:79], v[188:191], v[238:241], v[76:79]
	v_mfma_f32_16x16x32_bf16 v[72:75], v[196:199], v[238:241], v[72:75]
	v_mfma_f32_16x16x32_bf16 v[124:127], v[192:195], v[218:221], v[124:127]
	v_mfma_f32_16x16x32_bf16 v[120:123], v[200:203], v[218:221], v[120:123]
	v_mfma_f32_16x16x32_bf16 v[108:111], v[192:195], v[226:229], v[108:111]
	v_mfma_f32_16x16x32_bf16 v[104:107], v[200:203], v[226:229], v[104:107]
	v_mfma_f32_16x16x32_bf16 v[92:95], v[192:195], v[234:237], v[92:95]
	v_mfma_f32_16x16x32_bf16 v[88:91], v[200:203], v[234:237], v[88:91]
	v_mfma_f32_16x16x32_bf16 v[76:79], v[192:195], v[242:245], v[76:79]
	v_mfma_f32_16x16x32_bf16 v[72:75], v[200:203], v[242:245], v[72:75]
	s_setprio 0
	s_barrier
	s_add_i32 s42, s45, s53
	v_lshl_add_u64 v[168:169], v[168:169], 0, s[22:23]
	s_mov_b32 m0, s42
	ds_read_b128 v[214:217], v173 offset:49152
	ds_read_b128 v[218:221], v173 offset:50176
	ds_read_b128 v[222:225], v173 offset:51200
	ds_read_b128 v[226:229], v173 offset:52224
	ds_read_b128 v[230:233], v173 offset:53248
	ds_read_b128 v[234:237], v173 offset:54272
	ds_read_b128 v[238:241], v173 offset:55296
	ds_read_b128 v[242:245], v173 offset:56320
	global_load_lds_dwordx4 v[168:169], off
	s_add_i32 m0, s42, 0x2000
	s_add_u32 s38, s38, 0x80080
	v_lshl_add_u64 v[168:169], v[204:205], 0, s[22:23]
	s_addc_u32 s39, s39, 0
	s_add_i32 s42, s47, s53
	global_load_lds_dwordx4 v[168:169], off
	v_lshl_add_u64 v[168:169], s[38:39], 0, v[136:137]
	s_mov_b32 m0, s42
	s_nop 0
	global_load_lds_dwordx4 v[168:169], off
	v_lshl_add_u64 v[168:169], s[38:39], 0, v[140:141]
	s_add_i32 m0, s42, 0x2000
	s_nop 0
	global_load_lds_dwordx4 v[168:169], off
	s_cmp_eq_u32 s27, 28
	s_cbranch_scc0 .Lr306_nl
	v_lshl_add_u64 v[168:169], v[246:247], 0, s[22:23]
	s_mov_b32 m0, s61
	s_nop 0
	global_load_lds_dwordx4 v[168:169], off
	v_lshl_add_u64 v[168:169], v[248:249], 0, s[22:23]
	s_mov_b32 m0, s64
	s_nop 0
	global_load_lds_dwordx4 v[168:169], off
.Lr306_nl:
	s_waitcnt vmcnt(6)
	s_waitcnt lgkmcnt(0)
	s_barrier
	s_setprio 1
	s_waitcnt lgkmcnt(0)
	v_mfma_f32_16x16x32_bf16 v[68:71], v[160:163], v[214:217], v[68:71]
	v_mfma_f32_16x16x32_bf16 v[64:67], v[174:177], v[214:217], v[64:67]
	v_mfma_f32_16x16x32_bf16 v[52:55], v[160:163], v[222:225], v[52:55]
	v_mfma_f32_16x16x32_bf16 v[48:51], v[174:177], v[222:225], v[48:51]
	v_mfma_f32_16x16x32_bf16 v[36:39], v[160:163], v[230:233], v[36:39]
	v_mfma_f32_16x16x32_bf16 v[30:33], v[174:177], v[230:233], v[30:33]
	v_mfma_f32_16x16x32_bf16 v[18:21], v[160:163], v[238:241], v[18:21]
	v_mfma_f32_16x16x32_bf16 v[10:13], v[174:177], v[238:241], v[10:13]
	v_mfma_f32_16x16x32_bf16 v[68:71], v[164:167], v[218:221], v[68:71]
	v_mfma_f32_16x16x32_bf16 v[64:67], v[184:187], v[218:221], v[64:67]
	v_mfma_f32_16x16x32_bf16 v[52:55], v[164:167], v[226:229], v[52:55]
	v_mfma_f32_16x16x32_bf16 v[48:51], v[184:187], v[226:229], v[48:51]
	v_mfma_f32_16x16x32_bf16 v[36:39], v[164:167], v[234:237], v[36:39]
	v_mfma_f32_16x16x32_bf16 v[30:33], v[184:187], v[234:237], v[30:33]
	v_mfma_f32_16x16x32_bf16 v[18:21], v[164:167], v[242:245], v[18:21]
	v_mfma_f32_16x16x32_bf16 v[10:13], v[184:187], v[242:245], v[10:13]
	s_setprio 0
	s_setprio 1
	v_mfma_f32_16x16x32_bf16 v[60:63], v[188:191], v[214:217], v[60:63]
	v_mfma_f32_16x16x32_bf16 v[56:59], v[196:199], v[214:217], v[56:59]
	v_mfma_f32_16x16x32_bf16 v[44:47], v[188:191], v[222:225], v[44:47]
	v_mfma_f32_16x16x32_bf16 v[40:43], v[196:199], v[222:225], v[40:43]
	v_mfma_f32_16x16x32_bf16 v[26:29], v[188:191], v[230:233], v[26:29]
	v_mfma_f32_16x16x32_bf16 v[22:25], v[196:199], v[230:233], v[22:25]
	v_mfma_f32_16x16x32_bf16 v[6:9], v[188:191], v[238:241], v[6:9]
	v_mfma_f32_16x16x32_bf16 v[2:5], v[196:199], v[238:241], v[2:5]
	v_mfma_f32_16x16x32_bf16 v[60:63], v[192:195], v[218:221], v[60:63]
	v_mfma_f32_16x16x32_bf16 v[56:59], v[200:203], v[218:221], v[56:59]
	v_mfma_f32_16x16x32_bf16 v[44:47], v[192:195], v[226:229], v[44:47]
	v_mfma_f32_16x16x32_bf16 v[40:43], v[200:203], v[226:229], v[40:43]
	v_mfma_f32_16x16x32_bf16 v[26:29], v[192:195], v[234:237], v[26:29]
	v_mfma_f32_16x16x32_bf16 v[22:25], v[200:203], v[234:237], v[22:25]
	v_mfma_f32_16x16x32_bf16 v[6:9], v[192:195], v[242:245], v[6:9]
	v_mfma_f32_16x16x32_bf16 v[2:5], v[200:203], v[242:245], v[2:5]
	s_setprio 0
	s_barrier
	s_add_i32 s27, s27, 2
	s_add_u32 s36, s36, 0x100
	s_addc_u32 s37, s37, 0
	s_add_u32 s25, s25, 0x100
	s_addc_u32 s26, s26, 0
	s_cmp_gt_u32 s27, 29
	s_cbranch_scc0 .LBB0_306
	s_and_b64 vcc, exec, s[28:29]
	s_cbranch_vccz .LBB0_309
	s_barrier

.LBB0_1664:
	s_add_u32 s44, s42, 0xfff80080
	s_addc_u32 s45, s43, -1
	s_add_i32 s64, 0, 0x10000
	s_cmp_eq_u32 s61, 28
	s_cselect_b32 s47, s29, s45
	s_cselect_b32 s46, s53, s44
	v_add_u32_e32 v151, s64, v141
	s_cselect_b32 s45, s13, s60
	s_cselect_b32 s44, s54, s55
	s_add_i32 s67, 0, 0x14000
	ds_read_b128 v[162:165], v151
	ds_read_b128 v[166:169], v151 offset:1024
	ds_read_b128 v[170:173], v151 offset:2048
	ds_read_b128 v[174:177], v151 offset:3072
	v_add_u32_e32 v151, s67, v141
	ds_read_b128 v[184:187], v151
	ds_read_b128 v[188:191], v151 offset:1024
	ds_read_b128 v[192:195], v151 offset:2048
	ds_read_b128 v[196:199], v151 offset:3072
	ds_read_b128 v[200:203], v149
	ds_read_b128 v[214:217], v149 offset:1024
	ds_read_b128 v[218:221], v149 offset:2048
	ds_read_b128 v[222:225], v149 offset:3072
	ds_read_b128 v[226:229], v149 offset:4096
	ds_read_b128 v[230:233], v149 offset:5120
	ds_read_b128 v[234:237], v149 offset:6144
	ds_read_b128 v[238:241], v149 offset:7168
	s_cmp_lg_u32 s61, -2
	s_cbranch_scc0 .Lr1664_nf
	v_lshl_add_u64 v[158:159], v[242:243], 0, s[22:23]
	s_mov_b32 m0, s48
	s_nop 0
	global_load_lds_dwordx4 v[158:159], off
	v_lshl_add_u64 v[158:159], v[244:245], 0, s[22:23]
	s_mov_b32 m0, s49
	s_nop 0
	global_load_lds_dwordx4 v[158:159], off
.Lr1664_nf:
	v_lshl_add_u64 v[158:159], s[42:43], 0, v[142:143]
	s_add_i32 m0, s25, 0xc000
	s_nop 0
	global_load_lds_dwordx4 v[158:159], off
	v_lshl_add_u64 v[158:159], s[42:43], 0, v[144:145]
	s_add_i32 m0, s25, 0xe000
	s_nop 0
	global_load_lds_dwordx4 v[158:159], off
	s_waitcnt vmcnt(8)
	s_waitcnt lgkmcnt(0)
	s_barrier
	s_setprio 1
	s_waitcnt lgkmcnt(0)
	v_mfma_f32_16x16x32_bf16 v[132:135], v[162:165], v[200:203], v[132:135]
	v_mfma_f32_16x16x32_bf16 v[128:131], v[170:173], v[200:203], v[128:131]
	v_mfma_f32_16x16x32_bf16 v[116:119], v[162:165], v[218:221], v[116:119]
	v_mfma_f32_16x16x32_bf16 v[112:115], v[170:173], v[218:221], v[112:115]
	v_mfma_f32_16x16x32_bf16 v[100:103], v[162:165], v[226:229], v[100:103]
	v_mfma_f32_16x16x32_bf16 v[96:99], v[170:173], v[226:229], v[96:99]
	v_mfma_f32_16x16x32_bf16 v[84:87], v[162:165], v[234:237], v[84:87]
	v_mfma_f32_16x16x32_bf16 v[80:83], v[170:173], v[234:237], v[80:83]
	v_mfma_f32_16x16x32_bf16 v[132:135], v[166:169], v[214:217], v[132:135]
	v_mfma_f32_16x16x32_bf16 v[128:131], v[174:177], v[214:217], v[128:131]
	v_mfma_f32_16x16x32_bf16 v[116:119], v[166:169], v[222:225], v[116:119]
	v_mfma_f32_16x16x32_bf16 v[112:115], v[174:177], v[222:225], v[112:115]
	v_mfma_f32_16x16x32_bf16 v[100:103], v[166:169], v[230:233], v[100:103]
	v_mfma_f32_16x16x32_bf16 v[96:99], v[174:177], v[230:233], v[96:99]
	v_mfma_f32_16x16x32_bf16 v[84:87], v[166:169], v[238:241], v[84:87]
	v_mfma_f32_16x16x32_bf16 v[80:83], v[174:177], v[238:241], v[80:83]
	s_setprio 0
	s_setprio 1
	v_mfma_f32_16x16x32_bf16 v[124:127], v[184:187], v[200:203], v[124:127]
	v_mfma_f32_16x16x32_bf16 v[120:123], v[192:195], v[200:203], v[120:123]
	v_mfma_f32_16x16x32_bf16 v[108:111], v[184:187], v[218:221], v[108:111]
	v_mfma_f32_16x16x32_bf16 v[104:107], v[192:195], v[218:221], v[104:107]
	v_mfma_f32_16x16x32_bf16 v[92:95], v[184:187], v[226:229], v[92:95]
	v_mfma_f32_16x16x32_bf16 v[88:91], v[192:195], v[226:229], v[88:91]
	v_mfma_f32_16x16x32_bf16 v[76:79], v[184:187], v[234:237], v[76:79]
	v_mfma_f32_16x16x32_bf16 v[72:75], v[192:195], v[234:237], v[72:75]
	v_mfma_f32_16x16x32_bf16 v[124:127], v[188:191], v[214:217], v[124:127]
	v_mfma_f32_16x16x32_bf16 v[120:123], v[196:199], v[214:217], v[120:123]
	v_mfma_f32_16x16x32_bf16 v[108:111], v[188:191], v[222:225], v[108:111]
	v_mfma_f32_16x16x32_bf16 v[104:107], v[196:199], v[222:225], v[104:107]
	v_mfma_f32_16x16x32_bf16 v[92:95], v[188:191], v[230:233], v[92:95]
	v_mfma_f32_16x16x32_bf16 v[88:91], v[196:199], v[230:233], v[88:91]
	v_mfma_f32_16x16x32_bf16 v[76:79], v[188:191], v[238:241], v[76:79]
	v_mfma_f32_16x16x32_bf16 v[72:75], v[196:199], v[238:241], v[72:75]
	s_setprio 0
	s_barrier
	s_add_i32 s64, s64, s20
	v_lshl_add_u64 v[158:159], s[44:45], 0, v[34:35]
	s_mov_b32 m0, s64
	ds_read_b128 v[200:203], v149 offset:16384
	ds_read_b128 v[214:217], v149 offset:17408
	ds_read_b128 v[218:221], v149 offset:18432
	ds_read_b128 v[222:225], v149 offset:19456
	ds_read_b128 v[226:229], v149 offset:20480
	ds_read_b128 v[230:233], v149 offset:21504
	ds_read_b128 v[234:237], v149 offset:22528
	ds_read_b128 v[238:241], v149 offset:23552
	global_load_lds_dwordx4 v[158:159], off
	s_add_i32 m0, s64, 0x2000
	s_add_u32 s64, s44, 0x80000
	v_lshl_add_u64 v[204:205], s[44:45], 0, v[14:15]
	s_addc_u32 s65, s45, 0
	s_add_i32 s67, s67, s20
	global_load_lds_dwordx4 v[204:205], off
	v_lshl_add_u64 v[242:243], s[64:65], 0, v[34:35]
	s_mov_b32 m0, s67
	v_lshl_add_u64 v[244:245], s[46:47], 0, v[136:137]
	global_load_lds_dwordx4 v[242:243], off
	v_lshl_add_u64 v[242:243], s[64:65], 0, v[14:15]
	s_add_i32 m0, s67, 0x2000
	s_nop 0
	global_load_lds_dwordx4 v[242:243], off
	v_lshl_add_u64 v[242:243], s[46:47], 0, v[138:139]
	s_waitcnt vmcnt(6)
	s_waitcnt lgkmcnt(0)
	s_barrier
	s_setprio 1
	s_waitcnt lgkmcnt(0)
	v_mfma_f32_16x16x32_bf16 v[68:71], v[162:165], v[200:203], v[68:71]
	v_mfma_f32_16x16x32_bf16 v[64:67], v[170:173], v[200:203], v[64:67]
	v_mfma_f32_16x16x32_bf16 v[52:55], v[162:165], v[218:221], v[52:55]
	v_mfma_f32_16x16x32_bf16 v[48:51], v[170:173], v[218:221], v[48:51]
	v_mfma_f32_16x16x32_bf16 v[36:39], v[162:165], v[226:229], v[36:39]
	v_mfma_f32_16x16x32_bf16 v[30:33], v[170:173], v[226:229], v[30:33]
	v_mfma_f32_16x16x32_bf16 v[18:21], v[162:165], v[234:237], v[18:21]
	v_mfma_f32_16x16x32_bf16 v[10:13], v[170:173], v[234:237], v[10:13]
	v_mfma_f32_16x16x32_bf16 v[68:71], v[166:169], v[214:217], v[68:71]
	v_mfma_f32_16x16x32_bf16 v[64:67], v[174:177], v[214:217], v[64:67]
	v_mfma_f32_16x16x32_bf16 v[52:55], v[166:169], v[222:225], v[52:55]
	v_mfma_f32_16x16x32_bf16 v[48:51], v[174:177], v[222:225], v[48:51]
	v_mfma_f32_16x16x32_bf16 v[36:39], v[166:169], v[230:233], v[36:39]
	v_mfma_f32_16x16x32_bf16 v[30:33], v[174:177], v[230:233], v[30:33]
	v_mfma_f32_16x16x32_bf16 v[18:21], v[166:169], v[238:241], v[18:21]
	v_mfma_f32_16x16x32_bf16 v[10:13], v[174:177], v[238:241], v[10:13]
	s_setprio 0
	s_setprio 1
	v_mfma_f32_16x16x32_bf16 v[60:63], v[184:187], v[200:203], v[60:63]
	v_mfma_f32_16x16x32_bf16 v[56:59], v[192:195], v[200:203], v[56:59]
	v_mfma_f32_16x16x32_bf16 v[44:47], v[184:187], v[218:221], v[44:47]
	v_mfma_f32_16x16x32_bf16 v[40:43], v[192:195], v[218:221], v[40:43]
	v_mfma_f32_16x16x32_bf16 v[26:29], v[184:187], v[226:229], v[26:29]
	v_mfma_f32_16x16x32_bf16 v[22:25], v[192:195], v[226:229], v[22:25]
	v_mfma_f32_16x16x32_bf16 v[6:9], v[184:187], v[234:237], v[6:9]
	v_mfma_f32_16x16x32_bf16 v[2:5], v[192:195], v[234:237], v[2:5]
	v_mfma_f32_16x16x32_bf16 v[60:63], v[188:191], v[214:217], v[60:63]
	v_mfma_f32_16x16x32_bf16 v[56:59], v[196:199], v[214:217], v[56:59]
	v_mfma_f32_16x16x32_bf16 v[44:47], v[188:191], v[222:225], v[44:47]
	v_mfma_f32_16x16x32_bf16 v[40:43], v[196:199], v[222:225], v[40:43]
	v_mfma_f32_16x16x32_bf16 v[26:29], v[188:191], v[230:233], v[26:29]
	v_mfma_f32_16x16x32_bf16 v[22:25], v[196:199], v[230:233], v[22:25]
	v_mfma_f32_16x16x32_bf16 v[6:9], v[188:191], v[238:241], v[6:9]
	v_mfma_f32_16x16x32_bf16 v[2:5], v[196:199], v[238:241], v[2:5]
	s_setprio 0
	s_barrier
	s_add_i32 s64, 0, 0x18000
	v_add_u32_e32 v151, s64, v141
	s_add_i32 s65, 0, 0x1c000
	ds_read_b128 v[162:165], v151
	ds_read_b128 v[166:169], v151 offset:1024
	ds_read_b128 v[170:173], v151 offset:2048
	ds_read_b128 v[174:177], v151 offset:3072
	v_add_u32_e32 v151, s65, v141
	ds_read_b128 v[184:187], v151
	ds_read_b128 v[188:191], v151 offset:1024
	ds_read_b128 v[192:195], v151 offset:2048
	ds_read_b128 v[196:199], v151 offset:3072
	s_add_u32 s46, s46, 0x80000
	s_addc_u32 s47, s47, 0
	s_mov_b32 m0, s27
	v_lshl_add_u64 v[246:247], s[46:47], 0, v[138:139]
	ds_read_b128 v[200:203], v149 offset:32768
	ds_read_b128 v[214:217], v149 offset:33792
	ds_read_b128 v[218:221], v149 offset:34816
	ds_read_b128 v[222:225], v149 offset:35840
	ds_read_b128 v[226:229], v149 offset:36864
	ds_read_b128 v[230:233], v149 offset:37888
	ds_read_b128 v[234:237], v149 offset:38912
	ds_read_b128 v[238:241], v149 offset:39936
	s_mov_b32 m0, s25
	s_nop 0
	global_load_lds_dwordx4 v[242:243], off
	s_mov_b32 m0, s26
	s_nop 0
	global_load_lds_dwordx4 v[244:245], off
	s_mov_b32 m0, s27
	s_nop 0
	global_load_lds_dwordx4 v[246:247], off
	v_lshl_add_u64 v[246:247], s[46:47], 0, v[136:137]
	s_mov_b32 m0, s31
	s_nop 0
	global_load_lds_dwordx4 v[246:247], off
	s_waitcnt vmcnt(8)
	s_waitcnt lgkmcnt(0)
	s_barrier
	s_setprio 1
	s_waitcnt lgkmcnt(0)
	v_mfma_f32_16x16x32_bf16 v[132:135], v[162:165], v[200:203], v[132:135]
	v_mfma_f32_16x16x32_bf16 v[128:131], v[170:173], v[200:203], v[128:131]
	v_mfma_f32_16x16x32_bf16 v[116:119], v[162:165], v[218:221], v[116:119]
	v_mfma_f32_16x16x32_bf16 v[112:115], v[170:173], v[218:221], v[112:115]
	v_mfma_f32_16x16x32_bf16 v[100:103], v[162:165], v[226:229], v[100:103]
	v_mfma_f32_16x16x32_bf16 v[96:99], v[170:173], v[226:229], v[96:99]
	v_mfma_f32_16x16x32_bf16 v[84:87], v[162:165], v[234:237], v[84:87]
	v_mfma_f32_16x16x32_bf16 v[80:83], v[170:173], v[234:237], v[80:83]
	v_mfma_f32_16x16x32_bf16 v[132:135], v[166:169], v[214:217], v[132:135]
	v_mfma_f32_16x16x32_bf16 v[128:131], v[174:177], v[214:217], v[128:131]
	v_mfma_f32_16x16x32_bf16 v[116:119], v[166:169], v[222:225], v[116:119]
	v_mfma_f32_16x16x32_bf16 v[112:115], v[174:177], v[222:225], v[112:115]
	v_mfma_f32_16x16x32_bf16 v[100:103], v[166:169], v[230:233], v[100:103]
	v_mfma_f32_16x16x32_bf16 v[96:99], v[174:177], v[230:233], v[96:99]
	v_mfma_f32_16x16x32_bf16 v[84:87], v[166:169], v[238:241], v[84:87]
	v_mfma_f32_16x16x32_bf16 v[80:83], v[174:177], v[238:241], v[80:83]
	s_setprio 0
	s_setprio 1
	v_mfma_f32_16x16x32_bf16 v[124:127], v[184:187], v[200:203], v[124:127]
	v_mfma_f32_16x16x32_bf16 v[120:123], v[192:195], v[200:203], v[120:123]
	v_mfma_f32_16x16x32_bf16 v[108:111], v[184:187], v[218:221], v[108:111]
	v_mfma_f32_16x16x32_bf16 v[104:107], v[192:195], v[218:221], v[104:107]
	v_mfma_f32_16x16x32_bf16 v[92:95], v[184:187], v[226:229], v[92:95]
	v_mfma_f32_16x16x32_bf16 v[88:91], v[192:195], v[226:229], v[88:91]
	v_mfma_f32_16x16x32_bf16 v[76:79], v[184:187], v[234:237], v[76:79]
	v_mfma_f32_16x16x32_bf16 v[72:75], v[192:195], v[234:237], v[72:75]
	v_mfma_f32_16x16x32_bf16 v[124:127], v[188:191], v[214:217], v[124:127]
	v_mfma_f32_16x16x32_bf16 v[120:123], v[196:199], v[214:217], v[120:123]
	v_mfma_f32_16x16x32_bf16 v[108:111], v[188:191], v[222:225], v[108:111]
	v_mfma_f32_16x16x32_bf16 v[104:107], v[196:199], v[222:225], v[104:107]
	v_mfma_f32_16x16x32_bf16 v[92:95], v[188:191], v[230:233], v[92:95]
	v_mfma_f32_16x16x32_bf16 v[88:91], v[196:199], v[230:233], v[88:91]
	v_mfma_f32_16x16x32_bf16 v[76:79], v[188:191], v[238:241], v[76:79]
	v_mfma_f32_16x16x32_bf16 v[72:75], v[196:199], v[238:241], v[72:75]
	s_setprio 0
	s_barrier
	s_add_i32 s46, s64, s20
	v_lshl_add_u64 v[158:159], v[158:159], 0, s[22:23]
	s_mov_b32 m0, s46
	ds_read_b128 v[200:203], v149 offset:49152
	ds_read_b128 v[214:217], v149 offset:50176
	ds_read_b128 v[218:221], v149 offset:51200
	ds_read_b128 v[222:225], v149 offset:52224
	ds_read_b128 v[226:229], v149 offset:53248
	ds_read_b128 v[230:233], v149 offset:54272
	ds_read_b128 v[234:237], v149 offset:55296
	ds_read_b128 v[238:241], v149 offset:56320
	global_load_lds_dwordx4 v[158:159], off
	s_add_i32 m0, s46, 0x2000
	s_add_u32 s44, s44, 0x80080
	v_lshl_add_u64 v[158:159], v[204:205], 0, s[22:23]
	s_addc_u32 s45, s45, 0
	s_add_i32 s46, s65, s20
	global_load_lds_dwordx4 v[158:159], off
	v_lshl_add_u64 v[158:159], s[44:45], 0, v[34:35]
	s_mov_b32 m0, s46
	s_nop 0
	global_load_lds_dwordx4 v[158:159], off
	v_lshl_add_u64 v[158:159], s[44:45], 0, v[14:15]
	s_add_i32 m0, s46, 0x2000
	s_nop 0
	global_load_lds_dwordx4 v[158:159], off
	s_cmp_eq_u32 s61, 28
	s_cbranch_scc0 .Lr1664_nl
	v_lshl_add_u64 v[158:159], v[242:243], 0, s[22:23]
	s_mov_b32 m0, s48
	s_nop 0
	global_load_lds_dwordx4 v[158:159], off
	v_lshl_add_u64 v[158:159], v[244:245], 0, s[22:23]
	s_mov_b32 m0, s49
	s_nop 0
	global_load_lds_dwordx4 v[158:159], off
.Lr1664_nl:
	s_waitcnt vmcnt(6)
	s_waitcnt lgkmcnt(0)
	s_barrier
	s_setprio 1
	s_waitcnt lgkmcnt(0)
	v_mfma_f32_16x16x32_bf16 v[68:71], v[162:165], v[200:203], v[68:71]
	v_mfma_f32_16x16x32_bf16 v[64:67], v[170:173], v[200:203], v[64:67]
	v_mfma_f32_16x16x32_bf16 v[52:55], v[162:165], v[218:221], v[52:55]
	v_mfma_f32_16x16x32_bf16 v[48:51], v[170:173], v[218:221], v[48:51]
	v_mfma_f32_16x16x32_bf16 v[36:39], v[162:165], v[226:229], v[36:39]
	v_mfma_f32_16x16x32_bf16 v[30:33], v[170:173], v[226:229], v[30:33]
	v_mfma_f32_16x16x32_bf16 v[18:21], v[162:165], v[234:237], v[18:21]
	v_mfma_f32_16x16x32_bf16 v[10:13], v[170:173], v[234:237], v[10:13]
	v_mfma_f32_16x16x32_bf16 v[68:71], v[166:169], v[214:217], v[68:71]
	v_mfma_f32_16x16x32_bf16 v[64:67], v[174:177], v[214:217], v[64:67]
	v_mfma_f32_16x16x32_bf16 v[52:55], v[166:169], v[222:225], v[52:55]
	v_mfma_f32_16x16x32_bf16 v[48:51], v[174:177], v[222:225], v[48:51]
	v_mfma_f32_16x16x32_bf16 v[36:39], v[166:169], v[230:233], v[36:39]
	v_mfma_f32_16x16x32_bf16 v[30:33], v[174:177], v[230:233], v[30:33]
	v_mfma_f32_16x16x32_bf16 v[18:21], v[166:169], v[238:241], v[18:21]
	v_mfma_f32_16x16x32_bf16 v[10:13], v[174:177], v[238:241], v[10:13]
	s_setprio 0
	s_setprio 1
	v_mfma_f32_16x16x32_bf16 v[60:63], v[184:187], v[200:203], v[60:63]
	v_mfma_f32_16x16x32_bf16 v[56:59], v[192:195], v[200:203], v[56:59]
	v_mfma_f32_16x16x32_bf16 v[44:47], v[184:187], v[218:221], v[44:47]
	v_mfma_f32_16x16x32_bf16 v[40:43], v[192:195], v[218:221], v[40:43]
	v_mfma_f32_16x16x32_bf16 v[26:29], v[184:187], v[226:229], v[26:29]
	v_mfma_f32_16x16x32_bf16 v[22:25], v[192:195], v[226:229], v[22:25]
	v_mfma_f32_16x16x32_bf16 v[6:9], v[184:187], v[234:237], v[6:9]
	v_mfma_f32_16x16x32_bf16 v[2:5], v[192:195], v[234:237], v[2:5]
	v_mfma_f32_16x16x32_bf16 v[60:63], v[188:191], v[214:217], v[60:63]
	v_mfma_f32_16x16x32_bf16 v[56:59], v[196:199], v[214:217], v[56:59]
	v_mfma_f32_16x16x32_bf16 v[44:47], v[188:191], v[222:225], v[44:47]
	v_mfma_f32_16x16x32_bf16 v[40:43], v[196:199], v[222:225], v[40:43]
	v_mfma_f32_16x16x32_bf16 v[26:29], v[188:191], v[230:233], v[26:29]
	v_mfma_f32_16x16x32_bf16 v[22:25], v[196:199], v[230:233], v[22:25]
	v_mfma_f32_16x16x32_bf16 v[6:9], v[188:191], v[238:241], v[6:9]
	v_mfma_f32_16x16x32_bf16 v[2:5], v[196:199], v[238:241], v[2:5]
	s_setprio 0
	s_barrier
	s_add_i32 s61, s61, 2
	s_add_u32 s42, s42, 0x100
	s_addc_u32 s43, s43, 0
	s_add_u32 s55, s55, 0x100
	s_addc_u32 s60, s60, 0
	s_cmp_gt_u32 s61, 29
	s_cbranch_scc0 .LBB0_1664
	s_and_b64 vcc, exec, s[10:11]
	s_cbranch_vccz .LBB0_1667
	s_barrier
